# MLA attention: cross-half row max via v_permlane32_swap instead of ds_bpermute + lgkmcnt(0) (no longer drains the 8 in-flight V-fragment reads before softmax); V reads waited just before first PV MFMA
# speedup vs baseline: 1.0396x; 1.0043x over previous
; #define LAS __attribute__((address_space(3)))
; DI float xmax32(float v) { return fmaxf(v, __shfl_xor(v, 32)); }
; #define MLA_LOAD(k0) do { const char* kt_ = Kg + (size_t)(k0) * 384; const char* vt_ = Vg + (size_t)(k0) * 2; \
;                           _Pragma("unroll") for (int i = 0; i < 3; ++i) kreg[i] = *(const u32x4*)(kt_ + kgo + i * 8192); \
;                           _Pragma("unroll") for (int i = 0; i < 2; ++i) vreg[i] = *(const u32x4*)(vt_ + vgo[i]); } while (0)
; template <int NDB>
; DI void softmax_only(f32x16& sacc, float& m, float& l, f32x16 (&oacc)[NDB], bf16x8 (&pf)[2]) {
;     float mx = sacc[0];
; #pragma unroll
;     for (int i = 1; i < 16; ++i) mx = fmaxf(mx, sacc[i]);
;     mx = xmax32(mx);
; DI void mla_attn_phase(const Params& p, LAS unsigned char* lds) {
;     ...
;         for (int t = 0; t < NT; ++t) {
;             if (t + 1 < NT) MLA_LOAD((t + 1) * 64);
;             LAS unsigned char* kb = lds + (t & 1) * BUF;
; #pragma unroll
;             for (int blk = 0; blk < 2; ++blk) {
;                 bf16x8 kf[12];
;                 LAS const unsigned char* kp = kb + (blk * 32 + r) * KSTR + h * 16;
; #pragma unroll
;                 for (int ks = 0; ks < 4; ++ks) kf[ks] = *(LAS const bf16x8*)(kp + ks * 32);
;                 f32x16 sacc;
; #pragma unroll
;                 for (int i = 0; i < 16; ++i) sacc[i] = -m;
; #pragma unroll
;                 for (int kg = 0; kg < 3; ++kg) {
;                     if (kg < 2) {
; #pragma unroll
;                         for (int ks = 0; ks < 4; ++ks) kf[4 * (kg + 1) + ks] = *(LAS const bf16x8*)(kp + (4 * (kg + 1) + ks) * 32);
;                     }
; #pragma unroll
;                     for (int ks = 0; ks < 4; ++ks) sacc = __builtin_amdgcn_mfma_f32_32x32x16_bf16(kf[4 * kg + ks], qf[4 * kg + ks], sacc, 0, 0, 0);
;                 }
;                 bf16x8 vf[2][4], pf[2];
;                 load_vfrags<4, VSTR>(vf, kb + KBUF + r * VSTR + blk * 64 + h * 16);
;                 softmax_only<4>(sacc, m, l, oacc, pf);
; #pragma unroll
;                 for (int s2 = 0; s2 < 2; ++s2)
; #pragma unroll
;                     for (int db = 0; db < 4; ++db) oacc[db] = __builtin_amdgcn_mfma_f32_32x32x16_bf16(vf[s2][db], pf[s2], oacc[db], 0, 0, 0);
;             }
;             if (t + 1 < NT) MLA_STORE(lds + ((t + 1) & 1) * BUF);
;             __syncthreads();
.LBB1_1684:
	v_exp_f32_e32 v64, v64
	v_exp_f32_e32 v65, v65
	v_exp_f32_e32 v66, v66
	v_exp_f32_e32 v67, v67
	v_exp_f32_e32 v68, v68
	v_exp_f32_e32 v69, v69
	v_exp_f32_e32 v70, v70
	v_exp_f32_e32 v71, v71
	v_add_f32_e32 v181, 0, v64
	v_add_f32_e32 v181, v181, v65
	v_add_f32_e32 v181, v66, v181
	v_add_f32_e32 v181, v67, v181
	v_cvt_pk_bf16_f32 v64, v64, v65
	v_cvt_pk_bf16_f32 v65, v66, v67
	v_cvt_pk_bf16_f32 v66, v68, v69
	v_cvt_pk_bf16_f32 v67, v70, v71
	v_add_f32_e32 v181, v68, v181
	v_exp_f32_e32 v72, v72
	s_waitcnt lgkmcnt(0)
	v_mfma_f32_32x32x16_bf16 v[48:63], v[176:179], v[64:67], v[48:63]
	v_exp_f32_e32 v73, v73
	v_exp_f32_e32 v74, v74
	v_exp_f32_e32 v75, v75
	v_exp_f32_e32 v76, v76
	v_exp_f32_e32 v77, v77
	v_exp_f32_e32 v78, v78
	v_exp_f32_e32 v79, v79
	v_mfma_f32_32x32x16_bf16 v[32:47], v[172:175], v[64:67], v[32:47]
	v_add_f32_e32 v181, v69, v181
	s_add_i32 s2, s2, 1
	v_add_f32_e32 v181, v70, v181
	v_add_f32_e32 v181, v71, v181
	s_bitcmp1_b32 s2, 0
	v_add_f32_e32 v181, v72, v181
	v_cvt_pk_bf16_f32 v68, v72, v73
	v_mfma_f32_32x32x16_bf16 v[16:31], v[168:171], v[64:67], v[16:31]
	v_cvt_pk_bf16_f32 v69, v74, v75
	v_cvt_pk_bf16_f32 v70, v76, v77
	v_cvt_pk_bf16_f32 v71, v78, v79
	s_cselect_b32 s3, 0xac00, 0
	v_add_f32_e32 v181, v73, v181
	s_add_i32 s3, s3, 0
	v_add_f32_e32 v181, v74, v181
	v_mfma_f32_32x32x16_bf16 v[0:15], v[164:167], v[64:67], v[0:15]
	v_add_u32_e32 v64, s3, v230
	v_add_f32_e32 v181, v75, v181
	s_waitcnt vmcnt(0)
	ds_write_b128 v64, v[156:159]
	v_add_u32_e32 v64, s3, v231
	v_add_f32_e32 v181, v76, v181
	ds_write_b128 v64, v[152:155]
	v_add_u32_e32 v64, s3, v232
	v_mfma_f32_32x32x16_bf16 v[48:63], v[92:95], v[68:71], v[48:63]
	v_add_f32_e32 v181, v77, v181
	ds_write_b128 v64, v[160:163]
	v_add_u32_e32 v64, s3, v212
	v_add_f32_e32 v181, v78, v181
	v_add_u32_e32 v64, 0x6000, v64
	v_add_f32_e32 v181, v79, v181
	ds_write2_b64 v64, v[148:149], v[150:151] offset0:128 offset1:130
	v_mfma_f32_32x32x16_bf16 v[32:47], v[80:83], v[68:71], v[32:47]
	v_add_u32_e32 v64, s3, v214
	s_mov_b64 s[4:5], 0x6000
	v_add_f32_e32 v242, v180, v181
	v_add_u32_e32 v64, 0x6000, v64
	v_lshl_add_u64 v[222:223], v[222:223], 0, s[46:47]
	v_lshl_add_u64 v[224:225], v[224:225], 0, s[46:47]
	v_lshl_add_u64 v[226:227], v[226:227], 0, s[4:5]
	v_mfma_f32_32x32x16_bf16 v[16:31], v[84:87], v[68:71], v[16:31]
	s_cmp_eq_u32 s2, 63
	ds_write2_b64 v64, v[144:145], v[146:147] offset0:128 offset1:130
	s_waitcnt lgkmcnt(0)
	s_barrier
	v_mfma_f32_32x32x16_bf16 v[0:15], v[88:91], v[68:71], v[0:15]
	s_cbranch_scc1 .LBB1_1689
.LBB1_1685:
	v_lshl_add_u64 v[64:65], s[40:41], 0, v[226:227]
	v_add_co_u32_e32 v66, vcc, 0x40516000, v64
	s_bitcmp1_b32 s2, 0
	s_nop 0
	v_addc_co_u32_e32 v67, vcc, 0, v65, vcc
	global_load_dwordx4 v[156:159], v[66:67], off
	v_add_co_u32_e32 v66, vcc, 0x40518000, v64
	s_cselect_b32 s3, 0xac00, 0
	s_nop 0
	v_addc_co_u32_e32 v67, vcc, 0, v65, vcc
	v_add_co_u32_e32 v64, vcc, 0x4051a000, v64
	global_load_dwordx4 v[152:155], v[66:67], off
	s_nop 0
	v_addc_co_u32_e32 v65, vcc, 0, v65, vcc
	global_load_dwordx4 v[160:163], v[64:65], off
	v_lshl_add_u64 v[64:65], s[40:41], 0, v[224:225]
	global_load_dwordx4 v[148:151], v[64:65], off
	v_lshl_add_u64 v[64:65], s[40:41], 0, v[222:223]
	s_add_i32 s3, s3, 0
	global_load_dwordx4 v[144:147], v[64:65], off
	v_add_u32_e32 v64, s3, v206
	v_add_u32_e32 v244, v64, v213
	v_xor_b32_e32 v64, 0x80000000, v221
	v_add_u32_e32 v65, s3, v207
	v_mov_b32_e32 v78, v64
	v_mov_b32_e32 v79, v64
	v_add_u32_e32 v243, v65, v206
	ds_read_b128 v[164:167], v244
	ds_read_b128 v[168:171], v244 offset:32
	ds_read_b128 v[172:175], v244 offset:64
	ds_read_b128 v[176:179], v244 offset:96
	v_mov_b32_e32 v65, v64
	v_mov_b32_e32 v66, v64
	v_mov_b32_e32 v67, v64
	v_mov_b32_e32 v68, v64
	v_mov_b32_e32 v69, v64
	v_mov_b32_e32 v70, v64
	v_mov_b32_e32 v71, v64
	v_mov_b32_e32 v72, v64
	v_mov_b32_e32 v73, v64
	v_mov_b32_e32 v74, v64
	v_mov_b32_e32 v75, v64
	v_mov_b32_e32 v76, v64
	v_mov_b32_e32 v77, v64
	v_mov_b64_e32 v[94:95], v[78:79]
	v_mov_b64_e32 v[92:93], v[76:77]
	v_mov_b64_e32 v[90:91], v[74:75]
	v_mov_b64_e32 v[88:89], v[72:73]
	v_mov_b64_e32 v[86:87], v[70:71]
	v_mov_b64_e32 v[84:85], v[68:69]
	v_mov_b64_e32 v[82:83], v[66:67]
	v_mov_b64_e32 v[80:81], v[64:65]
	ds_read_b128 v[180:183], v244 offset:128
	ds_read_b128 v[184:187], v244 offset:160
	ds_read_b128 v[188:191], v244 offset:192
	ds_read_b128 v[192:195], v244 offset:224
	s_waitcnt lgkmcnt(7)
	v_mfma_f32_32x32x16_bf16 v[80:95], v[164:167], v[140:143], v[80:95]
	ds_read_b128 v[66:69], v244 offset:256
	ds_read_b128 v[70:73], v244 offset:288
	ds_read_b128 v[74:77], v244 offset:320
	ds_read_b128 v[164:167], v244 offset:352
	s_waitcnt lgkmcnt(10)
	v_mfma_f32_32x32x16_bf16 v[80:95], v[168:171], v[136:139], v[80:95]
	s_waitcnt lgkmcnt(9)
	v_mfma_f32_32x32x16_bf16 v[80:95], v[172:175], v[132:135], v[80:95]
	s_waitcnt lgkmcnt(8)
	v_mfma_f32_32x32x16_bf16 v[80:95], v[176:179], v[128:131], v[80:95]
	s_waitcnt lgkmcnt(7)
	v_mfma_f32_32x32x16_bf16 v[80:95], v[180:183], v[124:127], v[80:95]
	s_waitcnt lgkmcnt(6)
	v_mfma_f32_32x32x16_bf16 v[80:95], v[184:187], v[120:123], v[80:95]
	s_waitcnt lgkmcnt(5)
	v_mfma_f32_32x32x16_bf16 v[80:95], v[188:191], v[116:119], v[80:95]
	s_waitcnt lgkmcnt(4)
	v_mfma_f32_32x32x16_bf16 v[80:95], v[192:195], v[112:115], v[80:95]
	s_waitcnt lgkmcnt(3)
	v_mfma_f32_32x32x16_bf16 v[80:95], v[66:69], v[108:111], v[80:95]
	s_waitcnt lgkmcnt(2)
	v_mfma_f32_32x32x16_bf16 v[80:95], v[70:73], v[104:107], v[80:95]
	s_waitcnt lgkmcnt(1)
	v_mfma_f32_32x32x16_bf16 v[80:95], v[74:77], v[100:103], v[80:95]
	s_waitcnt lgkmcnt(0)
	v_mfma_f32_32x32x16_bf16 v[80:95], v[164:167], v[96:99], v[80:95]
	ds_read_b128 v[192:195], v243 offset:25600
	ds_read_b128 v[164:167], v243 offset:25632
	ds_read_b128 v[188:191], v243 offset:30208
	ds_read_b128 v[184:187], v243 offset:34816
	ds_read_b128 v[168:171], v243 offset:39424
	ds_read_b128 v[172:175], v243 offset:30240
	ds_read_b128 v[176:179], v243 offset:34848
	ds_read_b128 v[180:183], v243 offset:39456
	s_nop 3
	v_max_f32_e32 v65, v81, v81
	v_max_f32_e32 v66, v80, v80
	v_max_f32_e32 v65, v66, v65
	v_max3_f32 v65, v65, v82, v83
	v_max3_f32 v65, v65, v84, v85
	v_max3_f32 v65, v65, v86, v87
	v_max3_f32 v65, v65, v88, v89
	v_max3_f32 v65, v65, v90, v91
	v_max3_f32 v65, v65, v92, v93
	v_max3_f32 v65, v65, v94, v95
	v_mov_b32_e32 v66, v65
	s_nop 1
	v_permlane32_swap_b32_e32 v66, v65
	v_max_f32_e32 v65, v65, v66
	v_cmp_lt_f32_e32 vcc, s10, v65
	s_cbranch_vccz .LBB1_1687
; #define LAS __attribute__((address_space(3)))
; DI unsigned pack2(float a, float b) { f32x2 v = {a, b}; hwbf16x2 r = __builtin_convertvector(v, hwbf16x2); return __builtin_bit_cast(unsigned, r); }
; DI float fast_exp2(float x) { return __builtin_amdgcn_exp2f(x); }
; template <int NDB>
; DI void softmax_only(f32x16& sacc, float& m, float& l, f32x16 (&oacc)[NDB], bf16x8 (&pf)[2]) {
;     ...
;     if (__any(mx > 8.0f)) {
;         const float d = fmaxf(mx, 0.f), alpha = fast_exp2(-d);
;         l *= alpha; m += d;
; #pragma unroll
;         for (int i = 0; i < 16; ++i) sacc[i] -= d;
; #pragma unroll
;         for (int db = 0; db < NDB; ++db)
; #pragma unroll
;             for (int i = 0; i < 16; ++i) oacc[db][i] *= alpha;
;     }
;     float pv[16], ls = 0.f;
; #pragma unroll
;     for (int i = 0; i < 16; ++i) { pv[i] = fast_exp2(sacc[i]); ls += pv[i]; }
;     l += ls;
; #pragma unroll
;     for (int s2 = 0; s2 < 2; ++s2) {
;         u32x4 pw;
; #pragma unroll
;         for (int q = 0; q < 4; ++q) pw[q] = pack2(pv[8 * s2 + 2 * q], pv[8 * s2 + 2 * q + 1]);
;         pf[s2] = __builtin_bit_cast(bf16x8, pw);
;     }
; DI void mla_attn_phase(const Params& p, LAS unsigned char* lds) {
;     ...
;                 for (int kg = 0; kg < 3; ++kg) {
;                     if (kg < 2) {
; #pragma unroll
;                         for (int ks = 0; ks < 4; ++ks) kf[4 * (kg + 1) + ks] = *(LAS const bf16x8*)(kp + (4 * (kg + 1) + ks) * 32);
;                     }
; #pragma unroll
;                     for (int ks = 0; ks < 4; ++ks) sacc = __builtin_amdgcn_mfma_f32_32x32x16_bf16(kf[4 * kg + ks], qf[4 * kg + ks], sacc, 0, 0, 0);
;                 }
;                 bf16x8 vf[2][4], pf[2];
;                 load_vfrags<4, VSTR>(vf, kb + KBUF + r * VSTR + blk * 64 + h * 16);
;                 softmax_only<4>(sacc, m, l, oacc, pf);
; #pragma unroll
;                 for (int s2 = 0; s2 < 2; ++s2)
; #pragma unroll
;                     for (int db = 0; db < 4; ++db) oacc[db] = __builtin_amdgcn_mfma_f32_32x32x16_bf16(vf[s2][db], pf[s2], oacc[db], 0, 0, 0);
	v_max_f32_e32 v64, v65, v65
	v_max_f32_e32 v64, 0, v64
	v_exp_f32_e64 v66, -v64
	v_add_f32_e32 v221, v221, v64
	v_pk_add_f32 v[80:81], v[80:81], v[64:65] op_sel_hi:[1,0] neg_lo:[0,1] neg_hi:[0,1]
	v_pk_add_f32 v[82:83], v[82:83], v[64:65] op_sel_hi:[1,0] neg_lo:[0,1] neg_hi:[0,1]
	v_mul_f32_e32 v242, v242, v66
	v_pk_add_f32 v[84:85], v[84:85], v[64:65] op_sel_hi:[1,0] neg_lo:[0,1] neg_hi:[0,1]
	v_pk_add_f32 v[86:87], v[86:87], v[64:65] op_sel_hi:[1,0] neg_lo:[0,1] neg_hi:[0,1]
	v_pk_add_f32 v[88:89], v[88:89], v[64:65] op_sel_hi:[1,0] neg_lo:[0,1] neg_hi:[0,1]
	v_pk_add_f32 v[90:91], v[90:91], v[64:65] op_sel_hi:[1,0] neg_lo:[0,1] neg_hi:[0,1]
	v_pk_add_f32 v[92:93], v[92:93], v[64:65] op_sel_hi:[1,0] neg_lo:[0,1] neg_hi:[0,1]
	v_pk_add_f32 v[94:95], v[94:95], v[64:65] op_sel_hi:[1,0] neg_lo:[0,1] neg_hi:[0,1]
	v_pk_mul_f32 v[62:63], v[62:63], v[66:67] op_sel_hi:[1,0]
	v_pk_mul_f32 v[60:61], v[60:61], v[66:67] op_sel_hi:[1,0]
	v_pk_mul_f32 v[58:59], v[58:59], v[66:67] op_sel_hi:[1,0]
	v_pk_mul_f32 v[56:57], v[56:57], v[66:67] op_sel_hi:[1,0]
	v_pk_mul_f32 v[54:55], v[54:55], v[66:67] op_sel_hi:[1,0]
	v_pk_mul_f32 v[52:53], v[52:53], v[66:67] op_sel_hi:[1,0]
	v_pk_mul_f32 v[50:51], v[50:51], v[66:67] op_sel_hi:[1,0]
	v_pk_mul_f32 v[48:49], v[48:49], v[66:67] op_sel_hi:[1,0]
	v_pk_mul_f32 v[46:47], v[46:47], v[66:67] op_sel_hi:[1,0]
	v_pk_mul_f32 v[44:45], v[44:45], v[66:67] op_sel_hi:[1,0]
	v_pk_mul_f32 v[42:43], v[42:43], v[66:67] op_sel_hi:[1,0]
	v_pk_mul_f32 v[40:41], v[40:41], v[66:67] op_sel_hi:[1,0]
	v_pk_mul_f32 v[38:39], v[38:39], v[66:67] op_sel_hi:[1,0]
	v_pk_mul_f32 v[36:37], v[36:37], v[66:67] op_sel_hi:[1,0]
	v_pk_mul_f32 v[34:35], v[34:35], v[66:67] op_sel_hi:[1,0]
	v_pk_mul_f32 v[32:33], v[32:33], v[66:67] op_sel_hi:[1,0]
	v_pk_mul_f32 v[30:31], v[30:31], v[66:67] op_sel_hi:[1,0]
	v_pk_mul_f32 v[28:29], v[28:29], v[66:67] op_sel_hi:[1,0]
	v_pk_mul_f32 v[26:27], v[26:27], v[66:67] op_sel_hi:[1,0]
	v_pk_mul_f32 v[24:25], v[24:25], v[66:67] op_sel_hi:[1,0]
	v_pk_mul_f32 v[22:23], v[22:23], v[66:67] op_sel_hi:[1,0]
	v_pk_mul_f32 v[20:21], v[20:21], v[66:67] op_sel_hi:[1,0]
	v_pk_mul_f32 v[18:19], v[18:19], v[66:67] op_sel_hi:[1,0]
	v_pk_mul_f32 v[16:17], v[16:17], v[66:67] op_sel_hi:[1,0]
	v_pk_mul_f32 v[14:15], v[14:15], v[66:67] op_sel_hi:[1,0]
	v_pk_mul_f32 v[12:13], v[12:13], v[66:67] op_sel_hi:[1,0]
	v_pk_mul_f32 v[10:11], v[10:11], v[66:67] op_sel_hi:[1,0]
	v_pk_mul_f32 v[8:9], v[8:9], v[66:67] op_sel_hi:[1,0]
	v_pk_mul_f32 v[6:7], v[6:7], v[66:67] op_sel_hi:[1,0]
	v_pk_mul_f32 v[4:5], v[4:5], v[66:67] op_sel_hi:[1,0]
	v_pk_mul_f32 v[2:3], v[2:3], v[66:67] op_sel_hi:[1,0]
	v_pk_mul_f32 v[0:1], v[0:1], v[66:67] op_sel_hi:[1,0]
	v_xor_b32_e32 v64, 0x80000000, v221
.LBB1_1687:
	v_exp_f32_e32 v80, v80
	v_exp_f32_e32 v81, v81
	v_exp_f32_e32 v82, v82
	v_exp_f32_e32 v83, v83
	v_add_f32_e32 v245, 0, v80
	v_exp_f32_e32 v84, v84
	v_add_f32_e32 v245, v245, v81
	v_exp_f32_e32 v85, v85
	v_add_f32_e32 v245, v82, v245
	v_exp_f32_e32 v86, v86
	v_exp_f32_e32 v87, v87
	v_add_f32_e32 v245, v83, v245
	v_add_f32_e32 v245, v84, v245
	v_exp_f32_e32 v88, v88
	v_add_f32_e32 v245, v85, v245
	v_exp_f32_e32 v89, v89
	v_add_f32_e32 v245, v86, v245
	v_exp_f32_e32 v90, v90
	v_cvt_pk_bf16_f32 v80, v80, v81
	v_cvt_pk_bf16_f32 v81, v82, v83
	v_cvt_pk_bf16_f32 v82, v84, v85
	v_cvt_pk_bf16_f32 v83, v86, v87
	v_add_f32_e32 v245, v87, v245
	v_exp_f32_e32 v91, v91
	s_waitcnt lgkmcnt(0)
	v_mfma_f32_32x32x16_bf16 v[48:63], v[192:195], v[80:83], v[48:63]
	v_add_f32_e32 v245, v88, v245
	v_exp_f32_e32 v92, v92
	v_add_f32_e32 v245, v89, v245
	v_exp_f32_e32 v93, v93
	v_add_f32_e32 v245, v90, v245
	v_exp_f32_e32 v94, v94
	v_exp_f32_e32 v95, v95
	v_mfma_f32_32x32x16_bf16 v[32:47], v[188:191], v[80:83], v[32:47]
	v_add_f32_e32 v245, v91, v245
	v_add_f32_e32 v245, v92, v245
	v_add_f32_e32 v245, v93, v245
	v_mov_b32_e32 v65, v64
	v_mov_b32_e32 v66, v64
	v_mov_b32_e32 v67, v64
	v_mov_b32_e32 v68, v64
	v_mfma_f32_32x32x16_bf16 v[16:31], v[184:187], v[80:83], v[16:31]
	v_mov_b32_e32 v69, v64
	v_mov_b32_e32 v70, v64
	v_mov_b32_e32 v71, v64
	v_mov_b32_e32 v72, v64
	v_mov_b32_e32 v73, v64
	v_mov_b32_e32 v74, v64
	v_mov_b32_e32 v75, v64
	v_mfma_f32_32x32x16_bf16 v[0:15], v[168:171], v[80:83], v[0:15]
	v_mov_b32_e32 v76, v64
	v_mov_b32_e32 v77, v64
	v_mov_b32_e32 v78, v64
	v_mov_b32_e32 v79, v64
	v_add_f32_e32 v245, v94, v245
	v_cvt_pk_bf16_f32 v84, v88, v89
	v_cvt_pk_bf16_f32 v85, v90, v91
	v_cvt_pk_bf16_f32 v86, v92, v93
	v_cvt_pk_bf16_f32 v87, v94, v95
	v_add_f32_e32 v245, v95, v245
	s_nop 0
	v_mfma_f32_32x32x16_bf16 v[48:63], v[164:167], v[84:87], v[48:63]
	v_mfma_f32_32x32x16_bf16 v[32:47], v[172:175], v[84:87], v[32:47]
	v_mfma_f32_32x32x16_bf16 v[16:31], v[176:179], v[84:87], v[16:31]
	v_mfma_f32_32x32x16_bf16 v[0:15], v[180:183], v[84:87], v[0:15]
	ds_read_b128 v[80:83], v244 offset:12800
	ds_read_b128 v[84:87], v244 offset:12832
	ds_read_b128 v[88:91], v244 offset:12864
	ds_read_b128 v[92:95], v244 offset:12896
	ds_read_b128 v[164:167], v244 offset:12928
	ds_read_b128 v[168:171], v244 offset:12960
	ds_read_b128 v[172:175], v244 offset:12992
	ds_read_b128 v[176:179], v244 offset:13024
	v_add_f32_e32 v180, v242, v245
	s_waitcnt lgkmcnt(7)
	v_mfma_f32_32x32x16_bf16 v[64:79], v[80:83], v[140:143], v[64:79]
	s_waitcnt lgkmcnt(6)
	v_mfma_f32_32x32x16_bf16 v[64:79], v[84:87], v[136:139], v[64:79]
	s_waitcnt lgkmcnt(5)
	v_mfma_f32_32x32x16_bf16 v[64:79], v[88:91], v[132:135], v[64:79]
	s_waitcnt lgkmcnt(4)
	v_mfma_f32_32x32x16_bf16 v[64:79], v[92:95], v[128:131], v[64:79]
	ds_read_b128 v[80:83], v244 offset:13056
	ds_read_b128 v[84:87], v244 offset:13088
	ds_read_b128 v[88:91], v244 offset:13120
	ds_read_b128 v[92:95], v244 offset:13152
	s_waitcnt lgkmcnt(7)
; #define LAS __attribute__((address_space(3)))
; DI float xmax32(float v) { return fmaxf(v, __shfl_xor(v, 32)); }
; DI float fast_exp2(float x) { return __builtin_amdgcn_exp2f(x); }
; template <int NDB>
; DI void softmax_only(f32x16& sacc, float& m, float& l, f32x16 (&oacc)[NDB], bf16x8 (&pf)[2]) {
;     float mx = sacc[0];
; #pragma unroll
;     for (int i = 1; i < 16; ++i) mx = fmaxf(mx, sacc[i]);
;     mx = xmax32(mx);
;     if (__any(mx > 8.0f)) {
;         const float d = fmaxf(mx, 0.f), alpha = fast_exp2(-d);
;         l *= alpha; m += d;
; #pragma unroll
;         for (int i = 0; i < 16; ++i) sacc[i] -= d;
; #pragma unroll
;         for (int db = 0; db < NDB; ++db)
; #pragma unroll
;             for (int i = 0; i < 16; ++i) oacc[db][i] *= alpha;
;     }
; DI void mla_attn_phase(const Params& p, LAS unsigned char* lds) {
;     ...
;                 for (int kg = 0; kg < 3; ++kg) {
;                     if (kg < 2) {
; #pragma unroll
;                         for (int ks = 0; ks < 4; ++ks) kf[4 * (kg + 1) + ks] = *(LAS const bf16x8*)(kp + (4 * (kg + 1) + ks) * 32);
;                     }
; #pragma unroll
;                     for (int ks = 0; ks < 4; ++ks) sacc = __builtin_amdgcn_mfma_f32_32x32x16_bf16(kf[4 * kg + ks], qf[4 * kg + ks], sacc, 0, 0, 0);
;                 }
;                 bf16x8 vf[2][4], pf[2];
;                 load_vfrags<4, VSTR>(vf, kb + KBUF + r * VSTR + blk * 64 + h * 16);
;                 softmax_only<4>(sacc, m, l, oacc, pf);
	v_mfma_f32_32x32x16_bf16 v[64:79], v[164:167], v[124:127], v[64:79]
	s_waitcnt lgkmcnt(6)
	v_mfma_f32_32x32x16_bf16 v[64:79], v[168:171], v[120:123], v[64:79]
	s_waitcnt lgkmcnt(5)
	v_mfma_f32_32x32x16_bf16 v[64:79], v[172:175], v[116:119], v[64:79]
	s_waitcnt lgkmcnt(4)
	v_mfma_f32_32x32x16_bf16 v[64:79], v[176:179], v[112:115], v[64:79]
	s_waitcnt lgkmcnt(3)
	v_mfma_f32_32x32x16_bf16 v[64:79], v[80:83], v[108:111], v[64:79]
	s_waitcnt lgkmcnt(2)
	v_mfma_f32_32x32x16_bf16 v[64:79], v[84:87], v[104:107], v[64:79]
	s_waitcnt lgkmcnt(1)
	v_mfma_f32_32x32x16_bf16 v[64:79], v[88:91], v[100:103], v[64:79]
	s_waitcnt lgkmcnt(0)
	v_mfma_f32_32x32x16_bf16 v[64:79], v[92:95], v[96:99], v[64:79]
	ds_read_b128 v[176:179], v243 offset:25664
	ds_read_b128 v[92:95], v243 offset:25696
	ds_read_b128 v[172:175], v243 offset:30272
	ds_read_b128 v[168:171], v243 offset:34880
	ds_read_b128 v[164:167], v243 offset:39488
	ds_read_b128 v[80:83], v243 offset:30304
	ds_read_b128 v[84:87], v243 offset:34912
	ds_read_b128 v[88:91], v243 offset:39520
	s_nop 3
	v_max_f32_e32 v181, v65, v65
	v_max_f32_e32 v182, v64, v64
	v_max_f32_e32 v181, v182, v181
	v_max3_f32 v181, v181, v66, v67
	v_max3_f32 v181, v181, v68, v69
	v_max3_f32 v181, v181, v70, v71
	v_max3_f32 v181, v181, v72, v73
	v_max3_f32 v181, v181, v74, v75
	v_max3_f32 v181, v181, v76, v77
	v_max3_f32 v181, v181, v78, v79
	v_mov_b32_e32 v182, v181
	s_nop 1
	v_permlane32_swap_b32_e32 v182, v181
	v_max_f32_e32 v181, v181, v182
	v_cmp_lt_f32_e32 vcc, s10, v181
	s_cbranch_vccz .LBB1_1684
	v_max_f32_e32 v181, v181, v181
	v_max_f32_e32 v182, 0, v181
	v_exp_f32_e64 v184, -v182
	v_add_f32_e32 v221, v221, v182
	v_pk_add_f32 v[64:65], v[64:65], v[182:183] op_sel_hi:[1,0] neg_lo:[0,1] neg_hi:[0,1]
	v_pk_add_f32 v[66:67], v[66:67], v[182:183] op_sel_hi:[1,0] neg_lo:[0,1] neg_hi:[0,1]
	v_mul_f32_e32 v180, v180, v184
	v_pk_add_f32 v[68:69], v[68:69], v[182:183] op_sel_hi:[1,0] neg_lo:[0,1] neg_hi:[0,1]
	v_pk_add_f32 v[70:71], v[70:71], v[182:183] op_sel_hi:[1,0] neg_lo:[0,1] neg_hi:[0,1]
	v_pk_add_f32 v[72:73], v[72:73], v[182:183] op_sel_hi:[1,0] neg_lo:[0,1] neg_hi:[0,1]
	v_pk_add_f32 v[74:75], v[74:75], v[182:183] op_sel_hi:[1,0] neg_lo:[0,1] neg_hi:[0,1]
	v_pk_add_f32 v[76:77], v[76:77], v[182:183] op_sel_hi:[1,0] neg_lo:[0,1] neg_hi:[0,1]
	v_pk_add_f32 v[78:79], v[78:79], v[182:183] op_sel_hi:[1,0] neg_lo:[0,1] neg_hi:[0,1]
	v_pk_mul_f32 v[62:63], v[62:63], v[184:185] op_sel_hi:[1,0]
	v_pk_mul_f32 v[60:61], v[60:61], v[184:185] op_sel_hi:[1,0]
	v_pk_mul_f32 v[58:59], v[58:59], v[184:185] op_sel_hi:[1,0]
	v_pk_mul_f32 v[56:57], v[56:57], v[184:185] op_sel_hi:[1,0]
	v_pk_mul_f32 v[54:55], v[54:55], v[184:185] op_sel_hi:[1,0]
	v_pk_mul_f32 v[52:53], v[52:53], v[184:185] op_sel_hi:[1,0]
	v_pk_mul_f32 v[50:51], v[50:51], v[184:185] op_sel_hi:[1,0]
	v_pk_mul_f32 v[48:49], v[48:49], v[184:185] op_sel_hi:[1,0]
	v_pk_mul_f32 v[46:47], v[46:47], v[184:185] op_sel_hi:[1,0]
	v_pk_mul_f32 v[44:45], v[44:45], v[184:185] op_sel_hi:[1,0]
	v_pk_mul_f32 v[42:43], v[42:43], v[184:185] op_sel_hi:[1,0]
	v_pk_mul_f32 v[40:41], v[40:41], v[184:185] op_sel_hi:[1,0]
	v_pk_mul_f32 v[38:39], v[38:39], v[184:185] op_sel_hi:[1,0]
	v_pk_mul_f32 v[36:37], v[36:37], v[184:185] op_sel_hi:[1,0]
	v_pk_mul_f32 v[34:35], v[34:35], v[184:185] op_sel_hi:[1,0]
	v_pk_mul_f32 v[32:33], v[32:33], v[184:185] op_sel_hi:[1,0]
	v_pk_mul_f32 v[30:31], v[30:31], v[184:185] op_sel_hi:[1,0]
	v_pk_mul_f32 v[28:29], v[28:29], v[184:185] op_sel_hi:[1,0]
	v_pk_mul_f32 v[26:27], v[26:27], v[184:185] op_sel_hi:[1,0]
	v_pk_mul_f32 v[24:25], v[24:25], v[184:185] op_sel_hi:[1,0]
	v_pk_mul_f32 v[22:23], v[22:23], v[184:185] op_sel_hi:[1,0]
	v_pk_mul_f32 v[20:21], v[20:21], v[184:185] op_sel_hi:[1,0]
	v_pk_mul_f32 v[18:19], v[18:19], v[184:185] op_sel_hi:[1,0]
	v_pk_mul_f32 v[16:17], v[16:17], v[184:185] op_sel_hi:[1,0]
	v_pk_mul_f32 v[14:15], v[14:15], v[184:185] op_sel_hi:[1,0]
	v_pk_mul_f32 v[12:13], v[12:13], v[184:185] op_sel_hi:[1,0]
	v_pk_mul_f32 v[10:11], v[10:11], v[184:185] op_sel_hi:[1,0]
	v_pk_mul_f32 v[8:9], v[8:9], v[184:185] op_sel_hi:[1,0]
	v_pk_mul_f32 v[6:7], v[6:7], v[184:185] op_sel_hi:[1,0]
	v_pk_mul_f32 v[4:5], v[4:5], v[184:185] op_sel_hi:[1,0]
	v_pk_mul_f32 v[2:3], v[2:3], v[184:185] op_sel_hi:[1,0]
	v_pk_mul_f32 v[0:1], v[0:1], v[184:185] op_sel_hi:[1,0]
	s_branch .LBB1_1684
; #define LAS __attribute__((address_space(3)))
; DI float xmax32(float v) { return fmaxf(v, __shfl_xor(v, 32)); }
; DI float fast_exp2(float x) { return __builtin_amdgcn_exp2f(x); }
; template <int NDB>
; DI void softmax_only(f32x16& sacc, float& m, float& l, f32x16 (&oacc)[NDB], bf16x8 (&pf)[2]) {
;     float mx = sacc[0];
; #pragma unroll
;     for (int i = 1; i < 16; ++i) mx = fmaxf(mx, sacc[i]);
;     mx = xmax32(mx);
;     if (__any(mx > 8.0f)) {
;         const float d = fmaxf(mx, 0.f), alpha = fast_exp2(-d);
;         l *= alpha; m += d;
; #pragma unroll
;         for (int i = 0; i < 16; ++i) sacc[i] -= d;
; #pragma unroll
;         for (int db = 0; db < NDB; ++db)
; #pragma unroll
;             for (int i = 0; i < 16; ++i) oacc[db][i] *= alpha;
;     }
; DI void mla_attn_phase(const Params& p, LAS unsigned char* lds) {
;     ...
;         for (int t = 0; t < NT; ++t) {
;             if (t + 1 < NT) MLA_LOAD((t + 1) * 64);
;             LAS unsigned char* kb = lds + (t & 1) * BUF;
; #pragma unroll
;             for (int blk = 0; blk < 2; ++blk) {
;                 bf16x8 kf[12];
;                 LAS const unsigned char* kp = kb + (blk * 32 + r) * KSTR + h * 16;
; #pragma unroll
;                 for (int ks = 0; ks < 4; ++ks) kf[ks] = *(LAS const bf16x8*)(kp + ks * 32);
;                 f32x16 sacc;
; #pragma unroll
;                 for (int i = 0; i < 16; ++i) sacc[i] = -m;
; #pragma unroll
;                 for (int kg = 0; kg < 3; ++kg) {
;                     if (kg < 2) {
; #pragma unroll
;                         for (int ks = 0; ks < 4; ++ks) kf[4 * (kg + 1) + ks] = *(LAS const bf16x8*)(kp + (4 * (kg + 1) + ks) * 32);
;                     }
; #pragma unroll
;                     for (int ks = 0; ks < 4; ++ks) sacc = __builtin_amdgcn_mfma_f32_32x32x16_bf16(kf[4 * kg + ks], qf[4 * kg + ks], sacc, 0, 0, 0);
;                 }
;                 bf16x8 vf[2][4], pf[2];
;                 load_vfrags<4, VSTR>(vf, kb + KBUF + r * VSTR + blk * 64 + h * 16);
;                 softmax_only<4>(sacc, m, l, oacc, pf);
.LBB1_1689:
	ds_read_b128 v[144:147], v240 offset:44032
	ds_read_b128 v[148:151], v240 offset:44064
	v_xor_b32_e32 v64, 0x80000000, v221
	v_mov_b32_e32 v78, v64
	v_mov_b32_e32 v79, v64
	v_mov_b32_e32 v65, v64
	v_mov_b32_e32 v66, v64
	v_mov_b32_e32 v67, v64
	v_mov_b32_e32 v68, v64
	v_mov_b32_e32 v69, v64
	v_mov_b32_e32 v70, v64
	v_mov_b32_e32 v71, v64
	v_mov_b32_e32 v72, v64
	v_mov_b32_e32 v73, v64
	v_mov_b32_e32 v74, v64
	v_mov_b32_e32 v75, v64
	v_mov_b32_e32 v76, v64
	v_mov_b32_e32 v77, v64
	v_mov_b64_e32 v[94:95], v[78:79]
	v_mov_b64_e32 v[92:93], v[76:77]
	v_mov_b64_e32 v[90:91], v[74:75]
	v_mov_b64_e32 v[88:89], v[72:73]
	v_mov_b64_e32 v[86:87], v[70:71]
	v_mov_b64_e32 v[84:85], v[68:69]
	v_mov_b64_e32 v[82:83], v[66:67]
	v_mov_b64_e32 v[80:81], v[64:65]
	ds_read_b128 v[66:69], v240 offset:44096
	ds_read_b128 v[70:73], v240 offset:44128
	s_waitcnt lgkmcnt(3)
	v_mfma_f32_32x32x16_bf16 v[80:95], v[144:147], v[140:143], v[80:95]
	s_waitcnt lgkmcnt(2)
	v_mfma_f32_32x32x16_bf16 v[80:95], v[148:151], v[136:139], v[80:95]
	s_waitcnt lgkmcnt(1)
	v_mfma_f32_32x32x16_bf16 v[80:95], v[66:69], v[132:135], v[80:95]
	s_waitcnt lgkmcnt(0)
	v_mfma_f32_32x32x16_bf16 v[80:95], v[70:73], v[128:131], v[80:95]
	ds_read_b128 v[66:69], v240 offset:44160
	ds_read_b128 v[70:73], v240 offset:44192
	s_waitcnt lgkmcnt(1)
	v_mfma_f32_32x32x16_bf16 v[80:95], v[66:69], v[124:127], v[80:95]
	s_waitcnt lgkmcnt(0)
	v_mfma_f32_32x32x16_bf16 v[80:95], v[70:73], v[120:123], v[80:95]
	ds_read_b128 v[66:69], v240 offset:44224
	ds_read_b128 v[70:73], v240 offset:44256
	s_waitcnt lgkmcnt(1)
	v_mfma_f32_32x32x16_bf16 v[80:95], v[66:69], v[116:119], v[80:95]
	s_waitcnt lgkmcnt(0)
	v_mfma_f32_32x32x16_bf16 v[80:95], v[70:73], v[112:115], v[80:95]
	ds_read_b128 v[66:69], v240 offset:44288
	ds_read_b128 v[70:73], v240 offset:44320
	s_waitcnt lgkmcnt(1)
	v_mfma_f32_32x32x16_bf16 v[80:95], v[66:69], v[108:111], v[80:95]
	s_waitcnt lgkmcnt(0)
	v_mfma_f32_32x32x16_bf16 v[80:95], v[70:73], v[104:107], v[80:95]
	ds_read_b128 v[66:69], v240 offset:44352
	ds_read_b128 v[70:73], v240 offset:44384
	ds_read_b128 v[168:171], v241
	ds_read_b128 v[144:147], v241 offset:32
	ds_read_b128 v[164:167], v241 offset:4608
	ds_read_b128 v[148:151], v241 offset:4640
	ds_read_b128 v[172:175], v241 offset:9216
	ds_read_b128 v[152:155], v241 offset:9248
	ds_read_b128 v[160:163], v241 offset:13824
	ds_read_b128 v[156:159], v241 offset:13856
	s_waitcnt lgkmcnt(9)
	v_mfma_f32_32x32x16_bf16 v[80:95], v[66:69], v[100:103], v[80:95]
	s_waitcnt lgkmcnt(8)
	v_mfma_f32_32x32x16_bf16 v[80:95], v[70:73], v[96:99], v[80:95]
	s_nop 11
	v_max_f32_e32 v65, v81, v81
	v_max_f32_e32 v66, v80, v80
	v_max_f32_e32 v65, v66, v65
	v_max3_f32 v65, v65, v82, v83
	v_max3_f32 v65, v65, v84, v85
	v_max3_f32 v65, v65, v86, v87
	v_max3_f32 v65, v65, v88, v89
	v_max3_f32 v65, v65, v90, v91
	v_max3_f32 v65, v65, v92, v93
	v_max3_f32 v65, v65, v94, v95
	v_mov_b32_e32 v66, v65
	s_nop 1
	v_permlane32_swap_b32_e32 v66, v65
	v_max_f32_e32 v65, v65, v66
	v_cmp_lt_f32_e32 vcc, s10, v65
	s_cbranch_vccz .LBB1_1691
	v_max_f32_e32 v64, v65, v65
	v_max_f32_e32 v64, 0, v64
	v_exp_f32_e64 v66, -v64
	v_add_f32_e32 v65, v221, v64
	v_pk_add_f32 v[80:81], v[80:81], v[64:65] op_sel_hi:[1,0] neg_lo:[0,1] neg_hi:[0,1]
	v_pk_add_f32 v[82:83], v[82:83], v[64:65] op_sel_hi:[1,0] neg_lo:[0,1] neg_hi:[0,1]
	v_mul_f32_e32 v242, v242, v66
	v_pk_add_f32 v[84:85], v[84:85], v[64:65] op_sel_hi:[1,0] neg_lo:[0,1] neg_hi:[0,1]
	v_pk_add_f32 v[86:87], v[86:87], v[64:65] op_sel_hi:[1,0] neg_lo:[0,1] neg_hi:[0,1]
	v_pk_add_f32 v[88:89], v[88:89], v[64:65] op_sel_hi:[1,0] neg_lo:[0,1] neg_hi:[0,1]
	v_pk_add_f32 v[90:91], v[90:91], v[64:65] op_sel_hi:[1,0] neg_lo:[0,1] neg_hi:[0,1]
	v_pk_add_f32 v[92:93], v[92:93], v[64:65] op_sel_hi:[1,0] neg_lo:[0,1] neg_hi:[0,1]
	v_pk_add_f32 v[94:95], v[94:95], v[64:65] op_sel_hi:[1,0] neg_lo:[0,1] neg_hi:[0,1]
	v_pk_mul_f32 v[62:63], v[62:63], v[66:67] op_sel_hi:[1,0]
	v_pk_mul_f32 v[60:61], v[60:61], v[66:67] op_sel_hi:[1,0]
	v_pk_mul_f32 v[58:59], v[58:59], v[66:67] op_sel_hi:[1,0]
	v_pk_mul_f32 v[56:57], v[56:57], v[66:67] op_sel_hi:[1,0]
	v_pk_mul_f32 v[54:55], v[54:55], v[66:67] op_sel_hi:[1,0]
	v_pk_mul_f32 v[52:53], v[52:53], v[66:67] op_sel_hi:[1,0]
	v_pk_mul_f32 v[50:51], v[50:51], v[66:67] op_sel_hi:[1,0]
	v_pk_mul_f32 v[48:49], v[48:49], v[66:67] op_sel_hi:[1,0]
	v_pk_mul_f32 v[46:47], v[46:47], v[66:67] op_sel_hi:[1,0]
	v_pk_mul_f32 v[44:45], v[44:45], v[66:67] op_sel_hi:[1,0]
	v_pk_mul_f32 v[42:43], v[42:43], v[66:67] op_sel_hi:[1,0]
	v_pk_mul_f32 v[40:41], v[40:41], v[66:67] op_sel_hi:[1,0]
	v_pk_mul_f32 v[38:39], v[38:39], v[66:67] op_sel_hi:[1,0]
	v_pk_mul_f32 v[36:37], v[36:37], v[66:67] op_sel_hi:[1,0]
	v_pk_mul_f32 v[34:35], v[34:35], v[66:67] op_sel_hi:[1,0]
	v_pk_mul_f32 v[32:33], v[32:33], v[66:67] op_sel_hi:[1,0]
	v_pk_mul_f32 v[30:31], v[30:31], v[66:67] op_sel_hi:[1,0]
	v_pk_mul_f32 v[28:29], v[28:29], v[66:67] op_sel_hi:[1,0]
	v_pk_mul_f32 v[26:27], v[26:27], v[66:67] op_sel_hi:[1,0]
	v_pk_mul_f32 v[24:25], v[24:25], v[66:67] op_sel_hi:[1,0]
	v_pk_mul_f32 v[22:23], v[22:23], v[66:67] op_sel_hi:[1,0]
	v_pk_mul_f32 v[20:21], v[20:21], v[66:67] op_sel_hi:[1,0]
	v_pk_mul_f32 v[18:19], v[18:19], v[66:67] op_sel_hi:[1,0]
	v_pk_mul_f32 v[16:17], v[16:17], v[66:67] op_sel_hi:[1,0]
	v_pk_mul_f32 v[14:15], v[14:15], v[66:67] op_sel_hi:[1,0]
	v_pk_mul_f32 v[12:13], v[12:13], v[66:67] op_sel_hi:[1,0]
	v_pk_mul_f32 v[10:11], v[10:11], v[66:67] op_sel_hi:[1,0]
	v_pk_mul_f32 v[8:9], v[8:9], v[66:67] op_sel_hi:[1,0]
	v_pk_mul_f32 v[6:7], v[6:7], v[66:67] op_sel_hi:[1,0]
	v_pk_mul_f32 v[4:5], v[4:5], v[66:67] op_sel_hi:[1,0]
	v_pk_mul_f32 v[2:3], v[2:3], v[66:67] op_sel_hi:[1,0]
	v_pk_mul_f32 v[0:1], v[0:1], v[66:67] op_sel_hi:[1,0]
	v_xor_b32_e32 v64, 0x80000000, v65
; #define LAS __attribute__((address_space(3)))
; DI unsigned pack2(float a, float b) { f32x2 v = {a, b}; hwbf16x2 r = __builtin_convertvector(v, hwbf16x2); return __builtin_bit_cast(unsigned, r); }
; DI float fast_exp2(float x) { return __builtin_amdgcn_exp2f(x); }
; template <int NDB>
; DI void softmax_only(f32x16& sacc, float& m, float& l, f32x16 (&oacc)[NDB], bf16x8 (&pf)[2]) {
;     ...
;     float pv[16], ls = 0.f;
; #pragma unroll
;     for (int i = 0; i < 16; ++i) { pv[i] = fast_exp2(sacc[i]); ls += pv[i]; }
;     l += ls;
; #pragma unroll
;     for (int s2 = 0; s2 < 2; ++s2) {
;         u32x4 pw;
; #pragma unroll
;         for (int q = 0; q < 4; ++q) pw[q] = pack2(pv[8 * s2 + 2 * q], pv[8 * s2 + 2 * q + 1]);
;         pf[s2] = __builtin_bit_cast(bf16x8, pw);
;     }
; DI void mla_attn_phase(const Params& p, LAS unsigned char* lds) {
;     ...
; #pragma unroll
;                 for (int ks = 0; ks < 4; ++ks) kf[ks] = *(LAS const bf16x8*)(kp + ks * 32);
;                 f32x16 sacc;
; #pragma unroll
;                 for (int i = 0; i < 16; ++i) sacc[i] = -m;
; #pragma unroll
;                 for (int kg = 0; kg < 3; ++kg) {
;                     if (kg < 2) {
; #pragma unroll
;                         for (int ks = 0; ks < 4; ++ks) kf[4 * (kg + 1) + ks] = *(LAS const bf16x8*)(kp + (4 * (kg + 1) + ks) * 32);
;                     }
; #pragma unroll
;                     for (int ks = 0; ks < 4; ++ks) sacc = __builtin_amdgcn_mfma_f32_32x32x16_bf16(kf[4 * kg + ks], qf[4 * kg + ks], sacc, 0, 0, 0);
;                 }
;                 bf16x8 vf[2][4], pf[2];
;                 load_vfrags<4, VSTR>(vf, kb + KBUF + r * VSTR + blk * 64 + h * 16);
;                 softmax_only<4>(sacc, m, l, oacc, pf);
; #pragma unroll
;                 for (int s2 = 0; s2 < 2; ++s2)
; #pragma unroll
;                     for (int db = 0; db < 4; ++db) oacc[db] = __builtin_amdgcn_mfma_f32_32x32x16_bf16(vf[s2][db], pf[s2], oacc[db], 0, 0, 0);
.LBB1_1691:
	v_exp_f32_e32 v80, v80
	v_exp_f32_e32 v81, v81
	v_exp_f32_e32 v82, v82
	v_exp_f32_e32 v83, v83
	v_add_f32_e32 v176, 0, v80
	v_exp_f32_e32 v84, v84
	v_add_f32_e32 v176, v176, v81
	v_exp_f32_e32 v85, v85
	v_add_f32_e32 v176, v82, v176
	v_exp_f32_e32 v86, v86
	v_exp_f32_e32 v87, v87
	v_add_f32_e32 v176, v83, v176
	v_add_f32_e32 v176, v84, v176
	v_exp_f32_e32 v88, v88
	v_add_f32_e32 v176, v85, v176
	v_exp_f32_e32 v89, v89
	v_add_f32_e32 v176, v86, v176
	v_exp_f32_e32 v90, v90
	v_cvt_pk_bf16_f32 v80, v80, v81
	v_cvt_pk_bf16_f32 v81, v82, v83
	v_cvt_pk_bf16_f32 v82, v84, v85
	v_cvt_pk_bf16_f32 v83, v86, v87
	v_add_f32_e32 v176, v87, v176
	v_exp_f32_e32 v91, v91
	s_waitcnt lgkmcnt(0)
	v_mfma_f32_32x32x16_bf16 v[48:63], v[168:171], v[80:83], v[48:63]
	v_add_f32_e32 v176, v88, v176
	v_exp_f32_e32 v92, v92
	v_add_f32_e32 v176, v89, v176
	v_exp_f32_e32 v93, v93
	v_add_f32_e32 v176, v90, v176
	v_exp_f32_e32 v94, v94
	v_exp_f32_e32 v95, v95
	v_mfma_f32_32x32x16_bf16 v[32:47], v[164:167], v[80:83], v[32:47]
	v_add_f32_e32 v176, v91, v176
	v_add_f32_e32 v176, v92, v176
	v_add_f32_e32 v176, v93, v176
	v_mov_b32_e32 v65, v64
	v_mov_b32_e32 v66, v64
	v_mov_b32_e32 v67, v64
	v_mov_b32_e32 v68, v64
	v_mfma_f32_32x32x16_bf16 v[16:31], v[172:175], v[80:83], v[16:31]
	v_mov_b32_e32 v69, v64
	v_mov_b32_e32 v70, v64
	v_mov_b32_e32 v71, v64
	v_mov_b32_e32 v72, v64
	v_mov_b32_e32 v73, v64
	v_mov_b32_e32 v74, v64
	v_mov_b32_e32 v75, v64
	v_mfma_f32_32x32x16_bf16 v[0:15], v[160:163], v[80:83], v[0:15]
	v_mov_b32_e32 v76, v64
	v_mov_b32_e32 v77, v64
	v_mov_b32_e32 v78, v64
	v_mov_b32_e32 v79, v64
	v_add_f32_e32 v176, v94, v176
	v_cvt_pk_bf16_f32 v84, v88, v89
	v_cvt_pk_bf16_f32 v85, v90, v91
	v_cvt_pk_bf16_f32 v86, v92, v93
	v_cvt_pk_bf16_f32 v87, v94, v95
	v_add_f32_e32 v176, v95, v176
	s_nop 0
	v_mfma_f32_32x32x16_bf16 v[48:63], v[144:147], v[84:87], v[48:63]
	v_add_f32_e32 v144, v242, v176
	v_mfma_f32_32x32x16_bf16 v[32:47], v[148:151], v[84:87], v[32:47]
	v_mfma_f32_32x32x16_bf16 v[16:31], v[152:155], v[84:87], v[16:31]
	v_mfma_f32_32x32x16_bf16 v[0:15], v[156:159], v[84:87], v[0:15]
	ds_read_b128 v[80:83], v240 offset:56832
	ds_read_b128 v[84:87], v240 offset:56864
	ds_read_b128 v[88:91], v240 offset:56896
	ds_read_b128 v[92:95], v240 offset:56928
	ds_read_b128 v[146:149], v240 offset:56960
	ds_read_b128 v[150:153], v240 offset:56992
	ds_read_b128 v[154:157], v240 offset:57024
	ds_read_b128 v[158:161], v240 offset:57056
	s_waitcnt lgkmcnt(7)
	v_mfma_f32_32x32x16_bf16 v[64:79], v[80:83], v[140:143], v[64:79]
	s_waitcnt lgkmcnt(6)
	v_mfma_f32_32x32x16_bf16 v[64:79], v[84:87], v[136:139], v[64:79]
	s_waitcnt lgkmcnt(5)
	v_mfma_f32_32x32x16_bf16 v[64:79], v[88:91], v[132:135], v[64:79]
	s_waitcnt lgkmcnt(4)
	v_mfma_f32_32x32x16_bf16 v[64:79], v[92:95], v[128:131], v[64:79]
	ds_read_b128 v[80:83], v240 offset:57088
	ds_read_b128 v[84:87], v240 offset:57120
	ds_read_b128 v[88:91], v240 offset:57152
	ds_read_b128 v[92:95], v240 offset:57184
	s_waitcnt lgkmcnt(7)
	v_mfma_f32_32x32x16_bf16 v[64:79], v[146:149], v[124:127], v[64:79]
	s_waitcnt lgkmcnt(6)
	v_mfma_f32_32x32x16_bf16 v[64:79], v[150:153], v[120:123], v[64:79]
	s_waitcnt lgkmcnt(5)
	v_mfma_f32_32x32x16_bf16 v[64:79], v[154:157], v[116:119], v[64:79]
	s_waitcnt lgkmcnt(4)
	v_mfma_f32_32x32x16_bf16 v[64:79], v[158:161], v[112:115], v[64:79]
	s_waitcnt lgkmcnt(3)
	v_mfma_f32_32x32x16_bf16 v[64:79], v[80:83], v[108:111], v[64:79]
	s_waitcnt lgkmcnt(2)
	v_mfma_f32_32x32x16_bf16 v[64:79], v[84:87], v[104:107], v[64:79]
	s_waitcnt lgkmcnt(1)
	v_mfma_f32_32x32x16_bf16 v[64:79], v[88:91], v[100:103], v[64:79]
	s_waitcnt lgkmcnt(0)
	v_mfma_f32_32x32x16_bf16 v[64:79], v[92:95], v[96:99], v[64:79]
	ds_read_b128 v[108:111], v241 offset:64
	ds_read_b128 v[80:83], v241 offset:96
	ds_read_b128 v[104:107], v241 offset:4672
	ds_read_b128 v[84:87], v241 offset:9280
	ds_read_b128 v[88:91], v241 offset:13888
	ds_read_b128 v[92:95], v241 offset:4704
	ds_read_b128 v[96:99], v241 offset:9312
	ds_read_b128 v[100:103], v241 offset:13920
	s_nop 3
	v_max_f32_e32 v112, v65, v65
	v_max_f32_e32 v113, v64, v64
	v_max_f32_e32 v112, v113, v112
	v_max3_f32 v112, v112, v66, v67
	v_max3_f32 v112, v112, v68, v69
	v_max3_f32 v112, v112, v70, v71
	v_max3_f32 v112, v112, v72, v73
	v_max3_f32 v112, v112, v74, v75
	v_max3_f32 v112, v112, v76, v77
	v_max3_f32 v112, v112, v78, v79
	ds_bpermute_b32 v113, v234, v112
	s_waitcnt lgkmcnt(0)
	v_max_f32_e32 v113, v113, v113
	v_max_f32_e32 v112, v112, v113
	v_cmp_lt_f32_e32 vcc, s10, v112
	s_cbranch_vccz .LBB1_1682
; DI float fast_exp2(float x) { return __builtin_amdgcn_exp2f(x); }
; template <int NDB>
; DI void softmax_only(f32x16& sacc, float& m, float& l, f32x16 (&oacc)[NDB], bf16x8 (&pf)[2]) {
;     ...
;     if (__any(mx > 8.0f)) {
;         const float d = fmaxf(mx, 0.f), alpha = fast_exp2(-d);
;         l *= alpha; m += d;
; #pragma unroll
;         for (int i = 0; i < 16; ++i) sacc[i] -= d;
; #pragma unroll
;         for (int db = 0; db < NDB; ++db)
; #pragma unroll
;             for (int i = 0; i < 16; ++i) oacc[db][i] *= alpha;
;     }
	v_max_f32_e32 v112, v112, v112
	v_max_f32_e32 v112, 0, v112
	v_exp_f32_e64 v114, -v112
	v_pk_add_f32 v[64:65], v[64:65], v[112:113] op_sel_hi:[1,0] neg_lo:[0,1] neg_hi:[0,1]
	v_pk_add_f32 v[66:67], v[66:67], v[112:113] op_sel_hi:[1,0] neg_lo:[0,1] neg_hi:[0,1]
	v_pk_add_f32 v[68:69], v[68:69], v[112:113] op_sel_hi:[1,0] neg_lo:[0,1] neg_hi:[0,1]
	v_mul_f32_e32 v144, v144, v114
	v_pk_add_f32 v[70:71], v[70:71], v[112:113] op_sel_hi:[1,0] neg_lo:[0,1] neg_hi:[0,1]
	v_pk_add_f32 v[72:73], v[72:73], v[112:113] op_sel_hi:[1,0] neg_lo:[0,1] neg_hi:[0,1]
	v_pk_add_f32 v[74:75], v[74:75], v[112:113] op_sel_hi:[1,0] neg_lo:[0,1] neg_hi:[0,1]
	v_pk_add_f32 v[76:77], v[76:77], v[112:113] op_sel_hi:[1,0] neg_lo:[0,1] neg_hi:[0,1]
	v_pk_add_f32 v[78:79], v[78:79], v[112:113] op_sel_hi:[1,0] neg_lo:[0,1] neg_hi:[0,1]
	v_pk_mul_f32 v[62:63], v[62:63], v[114:115] op_sel_hi:[1,0]
	v_pk_mul_f32 v[60:61], v[60:61], v[114:115] op_sel_hi:[1,0]
	v_pk_mul_f32 v[58:59], v[58:59], v[114:115] op_sel_hi:[1,0]
	v_pk_mul_f32 v[56:57], v[56:57], v[114:115] op_sel_hi:[1,0]
	v_pk_mul_f32 v[54:55], v[54:55], v[114:115] op_sel_hi:[1,0]
	v_pk_mul_f32 v[52:53], v[52:53], v[114:115] op_sel_hi:[1,0]
	v_pk_mul_f32 v[50:51], v[50:51], v[114:115] op_sel_hi:[1,0]
	v_pk_mul_f32 v[48:49], v[48:49], v[114:115] op_sel_hi:[1,0]
	v_pk_mul_f32 v[46:47], v[46:47], v[114:115] op_sel_hi:[1,0]
	v_pk_mul_f32 v[44:45], v[44:45], v[114:115] op_sel_hi:[1,0]
	v_pk_mul_f32 v[42:43], v[42:43], v[114:115] op_sel_hi:[1,0]
	v_pk_mul_f32 v[40:41], v[40:41], v[114:115] op_sel_hi:[1,0]
	v_pk_mul_f32 v[38:39], v[38:39], v[114:115] op_sel_hi:[1,0]
	v_pk_mul_f32 v[36:37], v[36:37], v[114:115] op_sel_hi:[1,0]
	v_pk_mul_f32 v[34:35], v[34:35], v[114:115] op_sel_hi:[1,0]
	v_pk_mul_f32 v[32:33], v[32:33], v[114:115] op_sel_hi:[1,0]
	v_pk_mul_f32 v[30:31], v[30:31], v[114:115] op_sel_hi:[1,0]
	v_pk_mul_f32 v[28:29], v[28:29], v[114:115] op_sel_hi:[1,0]
	v_pk_mul_f32 v[26:27], v[26:27], v[114:115] op_sel_hi:[1,0]
	v_pk_mul_f32 v[24:25], v[24:25], v[114:115] op_sel_hi:[1,0]
	v_pk_mul_f32 v[22:23], v[22:23], v[114:115] op_sel_hi:[1,0]
	v_pk_mul_f32 v[20:21], v[20:21], v[114:115] op_sel_hi:[1,0]
	v_pk_mul_f32 v[18:19], v[18:19], v[114:115] op_sel_hi:[1,0]
	v_pk_mul_f32 v[16:17], v[16:17], v[114:115] op_sel_hi:[1,0]
	v_pk_mul_f32 v[14:15], v[14:15], v[114:115] op_sel_hi:[1,0]
	v_pk_mul_f32 v[12:13], v[12:13], v[114:115] op_sel_hi:[1,0]
	v_pk_mul_f32 v[10:11], v[10:11], v[114:115] op_sel_hi:[1,0]
	v_pk_mul_f32 v[8:9], v[8:9], v[114:115] op_sel_hi:[1,0]
	v_pk_mul_f32 v[6:7], v[6:7], v[114:115] op_sel_hi:[1,0]
	v_pk_mul_f32 v[4:5], v[4:5], v[114:115] op_sel_hi:[1,0]
	v_pk_mul_f32 v[2:3], v[2:3], v[114:115] op_sel_hi:[1,0]
	v_pk_mul_f32 v[0:1], v[0:1], v[114:115] op_sel_hi:[1,0]
	s_branch .LBB1_1682
